# all pipelined K-loops: the whole next-stage DMA issued right after the stage barrier (no pieces spread over MFMA groups)
# baseline (speedup 1.0000x reference)
; template <int EPI, int MI>
; DI void gemm_tile(const GemmDesc& g, int tm, int tn, char* smem) {
;     ...
;   const int tid = get_tid(), lane = tid & 63, wave = tid >> 6, r = lane & 31, hh = lane >> 5;
;   const int wm = wave >> 1, wn = wave & 1;
;   const int m0 = tm * BM, n0 = tn * 128;
;   const int nk = g.K >> 6;
;   f32x16 acc[MI][2];
; #pragma unroll
;   for (int a = 0; a < MI; ++a)
; #pragma unroll
;     for (int b = 0; b < 2; ++b)
; #pragma unroll
;       for (int i = 0; i < 16; ++i) acc[a][b][i] = 0.f;
;   const int srow = tid >> 3;
;   const int schunk = (tid & 7) ^ ((srow & 7) ^ ((srow >> 3) & 3));
;     ...
;   const int rowA = wm * (32 * MI) + r, rowB = wn * 64 + r;
;   const int hk = hh ^ ((r & 7) ^ ((r >> 3) & 3));
;     ...
;   G_GLDS(0, 0);
;   asm volatile("s_waitcnt vmcnt(0)" ::: "memory");
;   __syncthreads();
; template <int EPI, int MI>
; DI void gemm_phase(const GemmDesc& g, char* smem, int vb, int nvb) {
;     ...
;   for (int q = start; q < local; q += step) {
;     const int mg = q / per;
;     const int rem = q - mg * per;
;     const int tn = rem / PM;
;     const int tm = mbase + mg * PM + (rem - tn * PM);
;     gemm_tile<EPI, MI>(g, tm, tn, smem);
.LBB0_202:
	s_abs_i32 s1, s5
	v_readlane_b32 s15, v219, 45
	s_mul_hi_u32 s15, s1, s15
	v_readlane_b32 s18, v219, 44
	s_mul_i32 s16, s15, s18
	s_sub_i32 s1, s1, s16
	s_ashr_i32 s0, s5, 31
	s_add_i32 s16, s15, 1
	s_sub_i32 s17, s1, s18
	s_cmp_ge_u32 s1, s18
	s_cselect_b32 s15, s16, s15
	s_cselect_b32 s1, s17, s1
	s_add_i32 s16, s15, 1
	s_cmp_ge_u32 s1, s18
	s_cselect_b32 s1, s16, s15
	s_xor_b32 s1, s1, s0
	s_sub_i32 s15, s1, s0
	s_mul_i32 s16, s15, s18
	s_sub_i32 s16, s5, s16
	s_abs_i32 s18, s16
	v_readlane_b32 s19, v219, 46
	s_mul_hi_u32 s19, s18, s19
	v_readlane_b32 s42, v218, 32
	s_mul_i32 s38, s19, s42
	s_sub_i32 s18, s18, s38
	s_ashr_i32 s17, s16, 31
	s_add_i32 s38, s19, 1
	s_sub_i32 s39, s18, s42
	s_cmp_ge_u32 s18, s42
	s_cselect_b32 s19, s38, s19
	s_cselect_b32 s18, s39, s18
	s_add_i32 s38, s19, 1
	s_cmp_ge_u32 s18, s42
	s_cselect_b32 s18, s38, s19
	s_xor_b32 s18, s18, s17
	s_sub_i32 s39, s18, s17
	s_sub_i32 s15, s15, s39
	v_mov_b32_e32 v4, v132
	s_mul_i32 s15, s15, s42
	s_add_i32 s16, s16, s54
	s_add_i32 s38, s16, s15
	v_ashrrev_i32_e32 v97, 3, v4
	v_ashrrev_i32_e32 v120, 7, v4
	v_bfe_u32 v0, v4, 6, 2
	v_xor_b32_e32 v1, v97, v4
	s_mulk_i32 s38, 0xc0
	v_and_b32_e32 v121, 31, v4
	v_bitop3_b32 v2, v1, v0, 7 bitop3:0x6c
	v_mul_lo_u32 v0, v120, s6
	v_and_b32_e32 v115, 7, v4
	v_or_b32_e32 v5, v0, v121
	v_lshrrev_b32_e32 v0, 3, v4
	s_waitcnt vmcnt(10)
	v_add_u32_e32 v98, s38, v97
	v_bfe_u32 v122, v4, 5, 1
	v_bitop3_b32 v0, v0, v115, 3 bitop3:0x6c
	v_ashrrev_i32_e32 v99, 31, v98
	v_xor_b32_e32 v6, v0, v122
	v_lshlrev_b64 v[0:1], 11, v[98:99]
	v_readlane_b32 s42, v223, 59
	v_lshlrev_b32_e32 v99, 4, v4
	v_readlane_b32 s43, v223, 60
	v_lshlrev_b32_e32 v100, 4, v2
	v_lshl_add_u32 v2, s39, 7, v97
	v_add_u32_e32 v124, 0, v99
	v_lshl_add_u64 v[0:1], s[42:43], 0, v[0:1]
	v_mov_b32_e32 v101, v96
	v_ashrrev_i32_e32 v3, 31, v2
	v_readfirstlane_b32 s15, v124
	v_add_u32_e32 v125, 0x1000, v124
	v_lshl_add_u64 v[0:1], v[0:1], 0, v[100:101]
	v_lshlrev_b64 v[2:3], 11, v[2:3]
	s_mov_b32 m0, s15
	s_mov_b64 s[42:43], 0x10000
	v_readfirstlane_b32 s15, v125
	v_add_u32_e32 v126, 0x2000, v124
	s_waitcnt vmcnt(9)
	v_lshl_add_u64 v[102:103], s[70:71], 0, v[2:3]
	global_load_lds_dwordx4 v[0:1], off
	v_lshl_add_u64 v[2:3], v[0:1], 0, s[42:43]
	s_mov_b32 m0, s15
	s_mov_b64 s[44:45], 0x20000
	v_readfirstlane_b32 s15, v126
	v_add_u32_e32 v127, 0x3000, v124
	global_load_lds_dwordx4 v[2:3], off
	v_lshl_add_u64 v[2:3], v[0:1], 0, s[44:45]
	s_mov_b32 m0, s15
	s_mov_b64 s[46:47], 0x30000
	v_readfirstlane_b32 s15, v127
	v_add_u32_e32 v128, 0x4000, v124
	global_load_lds_dwordx4 v[2:3], off
	v_lshl_add_u64 v[2:3], v[0:1], 0, s[46:47]
	s_mov_b32 m0, s15
	s_mov_b64 s[52:53], 0x40000
	v_readfirstlane_b32 s15, v128
	v_add_u32_e32 v129, 0x5000, v124
	global_load_lds_dwordx4 v[2:3], off
	v_lshl_add_u64 v[2:3], v[0:1], 0, s[52:53]
	s_mov_b32 m0, s15
	s_mov_b64 s[52:53], 0x50000
	v_readfirstlane_b32 s15, v129
	v_add_u32_e32 v130, 0xc000, v124
	global_load_lds_dwordx4 v[2:3], off
	v_lshl_add_u64 v[0:1], v[0:1], 0, s[52:53]
	s_mov_b32 m0, s15
	v_readfirstlane_b32 s15, v130
	v_add_u32_e32 v131, 0xd000, v124
	global_load_lds_dwordx4 v[0:1], off
	v_lshl_add_u64 v[0:1], v[102:103], 0, v[100:101]
	s_mov_b32 m0, s15
	v_readfirstlane_b32 s15, v131
	v_add_u32_e32 v153, 0xe000, v124
	global_load_lds_dwordx4 v[0:1], off
	v_lshl_add_u64 v[2:3], v[0:1], 0, s[42:43]
	s_mov_b32 m0, s15
	v_readfirstlane_b32 s15, v153
	v_add_u32_e32 v154, 0xf000, v124
	global_load_lds_dwordx4 v[2:3], off
	v_lshl_add_u64 v[2:3], v[0:1], 0, s[44:45]
	s_mov_b32 m0, s15
	v_readfirstlane_b32 s15, v154
	global_load_lds_dwordx4 v[2:3], off
	v_lshl_add_u64 v[0:1], v[0:1], 0, s[46:47]
	s_mov_b32 m0, s15
	s_mul_i32 s0, s0, 43
	global_load_lds_dwordx4 v[0:1], off
	s_add_i32 s17, s17, s0
	s_sub_i32 s0, s17, s18
	s_mul_i32 s1, s1, 43
	s_sub_i32 s0, s0, s1
	v_readlane_b32 s1, v218, 33
	v_bfe_u32 v123, v4, 6, 1
	v_lshlrev_b32_e32 v0, 7, v121
	s_mul_i32 s0, s1, s0
	v_lshl_or_b32 v0, v123, 13, v0
	s_add_i32 s0, s0, s4
	v_add_u32_e32 v156, 0, v0
	v_add_u32_e32 v158, s10, v0
	v_add_u32_e32 v0, s0, v97
	v_ashrrev_i32_e32 v1, 31, v0
	s_waitcnt vmcnt(0)
	v_lshlrev_b64 v[0:1], 11, v[0:1]
	v_lshlrev_b32_e32 v157, 4, v6
	v_lshl_add_u64 v[104:105], s[70:71], 0, v[0:1]
	v_mov_b32_e32 v0, 0
	v_lshl_add_u32 v155, v5, 7, 0
	s_mov_b32 s15, 0
	v_mov_b32_e32 v1, v0
	v_mov_b32_e32 v2, v0
	v_mov_b32_e32 v3, v0
	v_mov_b32_e32 v4, v0
	v_mov_b32_e32 v5, v0
	v_mov_b32_e32 v6, v0
	v_mov_b32_e32 v7, v0
	v_mov_b32_e32 v8, v0
	v_mov_b32_e32 v9, v0
	v_mov_b32_e32 v10, v0
	v_mov_b32_e32 v11, v0
	v_mov_b32_e32 v12, v0
	v_mov_b32_e32 v13, v0
	v_mov_b32_e32 v14, v0
	v_mov_b32_e32 v15, v0
	v_mov_b32_e32 v16, v0
	v_mov_b32_e32 v17, v0
	v_mov_b32_e32 v18, v0
	v_mov_b32_e32 v19, v0
	v_mov_b32_e32 v20, v0
	v_mov_b32_e32 v21, v0
	v_mov_b32_e32 v22, v0
	v_mov_b32_e32 v23, v0
	v_mov_b32_e32 v24, v0
	v_mov_b32_e32 v25, v0
	v_mov_b32_e32 v26, v0
	v_mov_b32_e32 v27, v0
	v_mov_b32_e32 v28, v0
	v_mov_b32_e32 v29, v0
	v_mov_b32_e32 v30, v0
	v_mov_b32_e32 v31, v0
	v_mov_b32_e32 v32, v0
	v_mov_b32_e32 v33, v0
	v_mov_b32_e32 v34, v0
	v_mov_b32_e32 v35, v0
	v_mov_b32_e32 v36, v0
	v_mov_b32_e32 v37, v0
	v_mov_b32_e32 v38, v0
	v_mov_b32_e32 v39, v0
	v_mov_b32_e32 v40, v0
	v_mov_b32_e32 v41, v0
	v_mov_b32_e32 v42, v0
	v_mov_b32_e32 v43, v0
	v_mov_b32_e32 v44, v0
	v_mov_b32_e32 v45, v0
	v_mov_b32_e32 v46, v0
	v_mov_b32_e32 v47, v0
	v_mov_b32_e32 v48, v0
	s_waitcnt vmcnt(0)
; template <int EPI, int MI>
; DI void gemm_tile(const GemmDesc& g, int tm, int tn, char* smem) {
;     ...
;   f32x16 acc[MI][2];
; #pragma unroll
;   for (int a = 0; a < MI; ++a)
; #pragma unroll
;     for (int b = 0; b < 2; ++b)
; #pragma unroll
;       for (int i = 0; i < 16; ++i) acc[a][b][i] = 0.f;
;   const int srow = tid >> 3;
;   const int schunk = (tid & 7) ^ ((srow & 7) ^ ((srow >> 3) & 3));
;     ...
;   const int rowA = wm * (32 * MI) + r, rowB = wn * 64 + r;
;   const int hk = hh ^ ((r & 7) ^ ((r >> 3) & 3));
;     ...
;   G_GLDS(0, 0);
;   asm volatile("s_waitcnt vmcnt(0)" ::: "memory");
;   __syncthreads();
;   for (int kt = 0; kt < nk; kt += 2) {
;     if (kt + 1 < nk) G_GLDS(kt + 1, 1);
;     G_COMPUTE(0);
;     asm volatile("s_waitcnt vmcnt(0)" ::: "memory");
	v_mov_b32_e32 v49, v0
	v_mov_b32_e32 v50, v0
	v_mov_b32_e32 v51, v0
	v_mov_b32_e32 v52, v0
	v_mov_b32_e32 v53, v0
	v_mov_b32_e32 v54, v0
	v_mov_b32_e32 v55, v0
	v_mov_b32_e32 v56, v0
	v_mov_b32_e32 v57, v0
	v_mov_b32_e32 v58, v0
	v_mov_b32_e32 v59, v0
	v_mov_b32_e32 v60, v0
	v_mov_b32_e32 v61, v0
	v_mov_b32_e32 v62, v0
	v_mov_b32_e32 v63, v0
	v_mov_b32_e32 v64, v0
	v_mov_b32_e32 v65, v0
	v_mov_b32_e32 v66, v0
	v_mov_b32_e32 v67, v0
	v_mov_b32_e32 v68, v0
	v_mov_b32_e32 v69, v0
	v_mov_b32_e32 v70, v0
	v_mov_b32_e32 v71, v0
	v_mov_b32_e32 v72, v0
	v_mov_b32_e32 v73, v0
	v_mov_b32_e32 v74, v0
	v_mov_b32_e32 v75, v0
	v_mov_b32_e32 v76, v0
	v_mov_b32_e32 v77, v0
	v_mov_b32_e32 v78, v0
	v_mov_b32_e32 v79, v0
	v_mov_b32_e32 v80, v0
	v_mov_b32_e32 v81, v0
	v_mov_b32_e32 v82, v0
	v_mov_b32_e32 v83, v0
	v_mov_b32_e32 v84, v0
	v_mov_b32_e32 v85, v0
	v_mov_b32_e32 v86, v0
	v_mov_b32_e32 v87, v0
	v_mov_b32_e32 v88, v0
	v_mov_b32_e32 v89, v0
	v_mov_b32_e32 v90, v0
	v_mov_b32_e32 v91, v0
	v_mov_b32_e32 v92, v0
	v_mov_b32_e32 v93, v0
	v_mov_b32_e32 v94, v0
	v_mov_b32_e32 v95, v0
	v_xor_b32_e32 v159, 32, v157
	v_xor_b32_e32 v160, 64, v157
	v_xor_b32_e32 v161, 0x60, v157
	s_mov_b64 s[18:19], 0x80
	s_mov_b64 s[42:43], 0x10080
	v_add_u32_e32 v162, v155, v157
	v_add_u32_e32 v163, v155, v159
	v_add_u32_e32 v164, v155, v160
	v_add_u32_e32 v165, v155, v161
	v_add_u32_e32 v166, v156, v157
	v_add_u32_e32 v167, v156, v159
	v_add_u32_e32 v168, v156, v160
	v_add_u32_e32 v169, v156, v161
	v_add_u32_e32 v170, v158, v157
	v_add_u32_e32 v171, v158, v159
	v_add_u32_e32 v172, v158, v160
	v_add_u32_e32 v173, v158, v161
	v_lshl_add_u64 v[174:175], v[104:105], 0, v[100:101]
	v_lshl_add_u64 v[176:177], v[102:103], 0, v[100:101]
	v_readfirstlane_b32 s100, v124
	s_waitcnt vmcnt(0) lgkmcnt(0)
	s_barrier
	s_add_u32 m0, s100, 0x6000
	v_lshl_add_u64 v[106:107], v[174:175], 0, s[96:97]
	global_load_lds_dwordx4 v[106:107], off
	s_add_u32 m0, s100, 0x7000
	v_lshl_add_u64 v[106:107], v[174:175], 0, s[50:51]
	global_load_lds_dwordx4 v[106:107], off
	s_add_u32 m0, s100, 0x8000
	v_lshl_add_u64 v[106:107], v[174:175], 0, s[24:25]
	global_load_lds_dwordx4 v[106:107], off
	s_add_u32 m0, s100, 0x9000
	v_lshl_add_u64 v[106:107], v[174:175], 0, s[26:27]
	global_load_lds_dwordx4 v[106:107], off
	s_add_u32 m0, s100, 0xa000
	v_lshl_add_u64 v[106:107], v[174:175], 0, s[28:29]
	global_load_lds_dwordx4 v[106:107], off
	s_add_u32 m0, s100, 0xb000
	v_lshl_add_u64 v[106:107], v[174:175], 0, s[30:31]
	global_load_lds_dwordx4 v[106:107], off
	v_lshl_add_u64 v[174:175], v[174:175], 0, s[18:19]
	s_add_u32 m0, s100, 0x10000
	v_lshl_add_u64 v[106:107], v[176:177], 0, s[18:19]
	global_load_lds_dwordx4 v[106:107], off
	s_add_u32 m0, s100, 0x11000
	v_lshl_add_u64 v[106:107], v[176:177], 0, s[42:43]
	global_load_lds_dwordx4 v[106:107], off
	s_mov_b64 s[16:17], 0x20080
	s_add_u32 m0, s100, 0x12000
	v_lshl_add_u64 v[106:107], v[176:177], 0, s[16:17]
	global_load_lds_dwordx4 v[106:107], off
	s_mov_b64 s[16:17], 0x30080
	s_add_u32 m0, s100, 0x13000
	v_lshl_add_u64 v[106:107], v[176:177], 0, s[16:17]
	global_load_lds_dwordx4 v[106:107], off
	v_lshl_add_u64 v[176:177], v[176:177], 0, s[18:19]
	ds_read_b128 v[236:239], v166 offset:49152
	ds_read_b128 v[240:243], v166 offset:53248
	ds_read_b128 v[224:227], v162
	ds_read_b128 v[228:231], v162 offset:4096
	s_mov_b32 s15, 0
.Lga_loop:
	ds_read_b128 v[232:235], v162 offset:8192
	s_waitcnt lgkmcnt(2)
	v_mfma_f32_32x32x16_bf16 v[80:95], v[224:227], v[236:239], v[80:95]
	v_mfma_f32_32x32x16_bf16 v[64:79], v[224:227], v[240:243], v[64:79]
	ds_read_b128 v[244:247], v167 offset:49152
	ds_read_b128 v[248:251], v167 offset:53248
	ds_read_b128 v[224:227], v163
	s_waitcnt lgkmcnt(4)
	v_mfma_f32_32x32x16_bf16 v[48:63], v[228:231], v[236:239], v[48:63]
	v_mfma_f32_32x32x16_bf16 v[32:47], v[228:231], v[240:243], v[32:47]
	ds_read_b128 v[228:231], v163 offset:4096
	s_waitcnt lgkmcnt(4)
	v_mfma_f32_32x32x16_bf16 v[16:31], v[232:235], v[236:239], v[16:31]
	v_mfma_f32_32x32x16_bf16 v[0:15], v[232:235], v[240:243], v[0:15]
	ds_read_b128 v[232:235], v163 offset:8192
	s_waitcnt lgkmcnt(2)
	v_mfma_f32_32x32x16_bf16 v[80:95], v[224:227], v[244:247], v[80:95]
	v_mfma_f32_32x32x16_bf16 v[64:79], v[224:227], v[248:251], v[64:79]
	ds_read_b128 v[236:239], v168 offset:49152
	ds_read_b128 v[240:243], v168 offset:53248
	ds_read_b128 v[224:227], v164
	s_waitcnt lgkmcnt(4)
	v_mfma_f32_32x32x16_bf16 v[48:63], v[228:231], v[244:247], v[48:63]
	v_mfma_f32_32x32x16_bf16 v[32:47], v[228:231], v[248:251], v[32:47]
	ds_read_b128 v[228:231], v164 offset:4096
	s_waitcnt lgkmcnt(4)
	v_mfma_f32_32x32x16_bf16 v[16:31], v[232:235], v[244:247], v[16:31]
	v_mfma_f32_32x32x16_bf16 v[0:15], v[232:235], v[248:251], v[0:15]
	ds_read_b128 v[232:235], v164 offset:8192
	s_waitcnt lgkmcnt(2)
	v_mfma_f32_32x32x16_bf16 v[80:95], v[224:227], v[236:239], v[80:95]
	v_mfma_f32_32x32x16_bf16 v[64:79], v[224:227], v[240:243], v[64:79]
	ds_read_b128 v[244:247], v169 offset:49152
	ds_read_b128 v[248:251], v169 offset:53248
	ds_read_b128 v[224:227], v165
	s_waitcnt lgkmcnt(4)
	v_mfma_f32_32x32x16_bf16 v[48:63], v[228:231], v[236:239], v[48:63]
	v_mfma_f32_32x32x16_bf16 v[32:47], v[228:231], v[240:243], v[32:47]
	ds_read_b128 v[228:231], v165 offset:4096
	s_waitcnt lgkmcnt(4)
	v_mfma_f32_32x32x16_bf16 v[16:31], v[232:235], v[236:239], v[16:31]
	v_mfma_f32_32x32x16_bf16 v[0:15], v[232:235], v[240:243], v[0:15]
	ds_read_b128 v[232:235], v165 offset:8192
	s_waitcnt lgkmcnt(2)
	v_mfma_f32_32x32x16_bf16 v[80:95], v[224:227], v[244:247], v[80:95]
	v_mfma_f32_32x32x16_bf16 v[64:79], v[224:227], v[248:251], v[64:79]
	s_waitcnt lgkmcnt(0)
	s_waitcnt vmcnt(0)
	s_barrier
; template <int EPI, int MI>
; DI void gemm_tile(const GemmDesc& g, int tm, int tn, char* smem) {
;     ...
;   for (int kt = 0; kt < nk; kt += 2) {
;     if (kt + 1 < nk) G_GLDS(kt + 1, 1);
;     G_COMPUTE(0);
;     asm volatile("s_waitcnt vmcnt(0)" ::: "memory");
;     __syncthreads();
;     if (kt + 1 < nk) {
;       if (kt + 2 < nk) G_GLDS(kt + 2, 0);
;       G_COMPUTE(1);
;       asm volatile("s_waitcnt vmcnt(0)" ::: "memory");
;       __syncthreads();
;     }
	s_cmp_eq_u32 s15, 14
	s_cbranch_scc1 .Lga_noearly
	s_mov_b32 m0, s100
	v_lshl_add_u64 v[106:107], v[174:175], 0, s[96:97]
	global_load_lds_dwordx4 v[106:107], off
	s_add_u32 m0, s100, 0x1000
	v_lshl_add_u64 v[106:107], v[174:175], 0, s[50:51]
	global_load_lds_dwordx4 v[106:107], off
	s_add_u32 m0, s100, 0x2000
	v_lshl_add_u64 v[106:107], v[174:175], 0, s[24:25]
	global_load_lds_dwordx4 v[106:107], off
	s_add_u32 m0, s100, 0x3000
	v_lshl_add_u64 v[106:107], v[174:175], 0, s[26:27]
	global_load_lds_dwordx4 v[106:107], off
	s_add_u32 m0, s100, 0x4000
	v_lshl_add_u64 v[106:107], v[174:175], 0, s[28:29]
	global_load_lds_dwordx4 v[106:107], off
	s_add_u32 m0, s100, 0x5000
	v_lshl_add_u64 v[106:107], v[174:175], 0, s[30:31]
	global_load_lds_dwordx4 v[106:107], off
	v_lshl_add_u64 v[174:175], v[174:175], 0, s[18:19]
	s_add_u32 m0, s100, 0xc000
	v_lshl_add_u64 v[106:107], v[176:177], 0, s[18:19]
	global_load_lds_dwordx4 v[106:107], off
	s_add_u32 m0, s100, 0xd000
	v_lshl_add_u64 v[106:107], v[176:177], 0, s[42:43]
	global_load_lds_dwordx4 v[106:107], off
	s_mov_b64 s[16:17], 0x20080
	s_add_u32 m0, s100, 0xe000
	v_lshl_add_u64 v[106:107], v[176:177], 0, s[16:17]
	global_load_lds_dwordx4 v[106:107], off
	s_mov_b64 s[16:17], 0x30080
	s_add_u32 m0, s100, 0xf000
	v_lshl_add_u64 v[106:107], v[176:177], 0, s[16:17]
	global_load_lds_dwordx4 v[106:107], off
	v_lshl_add_u64 v[176:177], v[176:177], 0, s[18:19]
.Lga_noearly:
	ds_read_b128 v[236:239], v170
	ds_read_b128 v[240:243], v170 offset:4096
	ds_read_b128 v[224:227], v162 offset:24576
	v_mfma_f32_32x32x16_bf16 v[48:63], v[228:231], v[244:247], v[48:63]
	v_mfma_f32_32x32x16_bf16 v[32:47], v[228:231], v[248:251], v[32:47]
	ds_read_b128 v[228:231], v162 offset:28672
	v_mfma_f32_32x32x16_bf16 v[16:31], v[232:235], v[244:247], v[16:31]
	v_mfma_f32_32x32x16_bf16 v[0:15], v[232:235], v[248:251], v[0:15]
	s_cmp_eq_u32 s15, 14
	s_cbranch_scc1 .Lga_last
	ds_read_b128 v[232:235], v162 offset:32768
	s_waitcnt lgkmcnt(2)
	v_mfma_f32_32x32x16_bf16 v[80:95], v[224:227], v[236:239], v[80:95]
	v_mfma_f32_32x32x16_bf16 v[64:79], v[224:227], v[240:243], v[64:79]
	ds_read_b128 v[244:247], v171
	ds_read_b128 v[248:251], v171 offset:4096
	ds_read_b128 v[224:227], v163 offset:24576
	s_waitcnt lgkmcnt(4)
	v_mfma_f32_32x32x16_bf16 v[48:63], v[228:231], v[236:239], v[48:63]
	v_mfma_f32_32x32x16_bf16 v[32:47], v[228:231], v[240:243], v[32:47]
	ds_read_b128 v[228:231], v163 offset:28672
	s_waitcnt lgkmcnt(4)
	v_mfma_f32_32x32x16_bf16 v[16:31], v[232:235], v[236:239], v[16:31]
	v_mfma_f32_32x32x16_bf16 v[0:15], v[232:235], v[240:243], v[0:15]
	ds_read_b128 v[232:235], v163 offset:32768
	s_waitcnt lgkmcnt(2)
	v_mfma_f32_32x32x16_bf16 v[80:95], v[224:227], v[244:247], v[80:95]
	v_mfma_f32_32x32x16_bf16 v[64:79], v[224:227], v[248:251], v[64:79]
	ds_read_b128 v[236:239], v172
	ds_read_b128 v[240:243], v172 offset:4096
	ds_read_b128 v[224:227], v164 offset:24576
	s_waitcnt lgkmcnt(4)
	v_mfma_f32_32x32x16_bf16 v[48:63], v[228:231], v[244:247], v[48:63]
	v_mfma_f32_32x32x16_bf16 v[32:47], v[228:231], v[248:251], v[32:47]
	ds_read_b128 v[228:231], v164 offset:28672
	s_waitcnt lgkmcnt(4)
	v_mfma_f32_32x32x16_bf16 v[16:31], v[232:235], v[244:247], v[16:31]
	v_mfma_f32_32x32x16_bf16 v[0:15], v[232:235], v[248:251], v[0:15]
	ds_read_b128 v[232:235], v164 offset:32768
	s_waitcnt lgkmcnt(2)
	v_mfma_f32_32x32x16_bf16 v[80:95], v[224:227], v[236:239], v[80:95]
	v_mfma_f32_32x32x16_bf16 v[64:79], v[224:227], v[240:243], v[64:79]
	ds_read_b128 v[244:247], v173
	ds_read_b128 v[248:251], v173 offset:4096
	ds_read_b128 v[224:227], v165 offset:24576
	s_waitcnt lgkmcnt(4)
	v_mfma_f32_32x32x16_bf16 v[48:63], v[228:231], v[236:239], v[48:63]
	v_mfma_f32_32x32x16_bf16 v[32:47], v[228:231], v[240:243], v[32:47]
	ds_read_b128 v[228:231], v165 offset:28672
	s_waitcnt lgkmcnt(4)
	v_mfma_f32_32x32x16_bf16 v[16:31], v[232:235], v[236:239], v[16:31]
	v_mfma_f32_32x32x16_bf16 v[0:15], v[232:235], v[240:243], v[0:15]
	ds_read_b128 v[232:235], v165 offset:32768
	s_waitcnt lgkmcnt(2)
	v_mfma_f32_32x32x16_bf16 v[80:95], v[224:227], v[244:247], v[80:95]
	v_mfma_f32_32x32x16_bf16 v[64:79], v[224:227], v[248:251], v[64:79]
	s_waitcnt lgkmcnt(0)
	s_waitcnt vmcnt(0)
	s_barrier
	s_add_u32 m0, s100, 0x6000
	v_lshl_add_u64 v[106:107], v[174:175], 0, s[96:97]
	global_load_lds_dwordx4 v[106:107], off
	s_add_u32 m0, s100, 0x7000
	v_lshl_add_u64 v[106:107], v[174:175], 0, s[50:51]
	global_load_lds_dwordx4 v[106:107], off
	s_add_u32 m0, s100, 0x8000
	v_lshl_add_u64 v[106:107], v[174:175], 0, s[24:25]
	global_load_lds_dwordx4 v[106:107], off
	s_add_u32 m0, s100, 0x9000
	v_lshl_add_u64 v[106:107], v[174:175], 0, s[26:27]
	global_load_lds_dwordx4 v[106:107], off
	s_add_u32 m0, s100, 0xa000
	v_lshl_add_u64 v[106:107], v[174:175], 0, s[28:29]
	global_load_lds_dwordx4 v[106:107], off
	s_add_u32 m0, s100, 0xb000
	v_lshl_add_u64 v[106:107], v[174:175], 0, s[30:31]
	global_load_lds_dwordx4 v[106:107], off
	v_lshl_add_u64 v[174:175], v[174:175], 0, s[18:19]
	s_add_u32 m0, s100, 0x10000
	v_lshl_add_u64 v[106:107], v[176:177], 0, s[18:19]
	global_load_lds_dwordx4 v[106:107], off
	s_add_u32 m0, s100, 0x11000
	v_lshl_add_u64 v[106:107], v[176:177], 0, s[42:43]
	global_load_lds_dwordx4 v[106:107], off
	s_mov_b64 s[16:17], 0x20080
	s_add_u32 m0, s100, 0x12000
	v_lshl_add_u64 v[106:107], v[176:177], 0, s[16:17]
	global_load_lds_dwordx4 v[106:107], off
	s_mov_b64 s[16:17], 0x30080
	s_add_u32 m0, s100, 0x13000
	v_lshl_add_u64 v[106:107], v[176:177], 0, s[16:17]
	global_load_lds_dwordx4 v[106:107], off
	v_lshl_add_u64 v[176:177], v[176:177], 0, s[18:19]
	ds_read_b128 v[236:239], v166 offset:49152
	ds_read_b128 v[240:243], v166 offset:53248
	ds_read_b128 v[224:227], v162
	v_mfma_f32_32x32x16_bf16 v[48:63], v[228:231], v[244:247], v[48:63]
	v_mfma_f32_32x32x16_bf16 v[32:47], v[228:231], v[248:251], v[32:47]
	ds_read_b128 v[228:231], v162 offset:4096
	v_mfma_f32_32x32x16_bf16 v[16:31], v[232:235], v[244:247], v[16:31]
	v_mfma_f32_32x32x16_bf16 v[0:15], v[232:235], v[248:251], v[0:15]
	s_add_u32 s15, s15, 2
	s_branch .Lga_loop

; template <int EPI, int MI>
; DI void gemm_tile(const GemmDesc& g, int tm, int tn, char* smem) {
;     ...
;   const int tid = get_tid(), lane = tid & 63, wave = tid >> 6, r = lane & 31, hh = lane >> 5;
;   const int wm = wave >> 1, wn = wave & 1;
;   const int m0 = tm * BM, n0 = tn * 128;
;   const int nk = g.K >> 6;
;   f32x16 acc[MI][2];
; #pragma unroll
;   for (int a = 0; a < MI; ++a)
; #pragma unroll
;     for (int b = 0; b < 2; ++b)
; #pragma unroll
;       for (int i = 0; i < 16; ++i) acc[a][b][i] = 0.f;
;   const int srow = tid >> 3;
;   const int schunk = (tid & 7) ^ ((srow & 7) ^ ((srow >> 3) & 3));
;     ...
;   const int rowA = wm * (32 * MI) + r, rowB = wn * 64 + r;
;   const int hk = hh ^ ((r & 7) ^ ((r >> 3) & 3));
;     ...
;   G_GLDS(0, 0);
;   asm volatile("s_waitcnt vmcnt(0)" ::: "memory");
;   __syncthreads();
; template <int EPI, int MI>
; DI void gemm_phase(const GemmDesc& g, char* smem, int vb, int nvb) {
;     ...
;   for (int q = start; q < local; q += step) {
;     const int mg = q / per;
;     const int rem = q - mg * per;
;     const int tn = rem / PM;
;     const int tm = mbase + mg * PM + (rem - tn * PM);
;     gemm_tile<EPI, MI>(g, tm, tn, smem);
.LBB0_371:
	s_abs_i32 s1, s47
	s_mul_hi_u32 s4, s1, s45
	s_mul_i32 s5, s4, s43
	s_sub_i32 s1, s1, s5
	s_ashr_i32 s0, s47, 31
	s_add_i32 s5, s4, 1
	s_sub_i32 s15, s1, s43
	s_cmp_ge_u32 s1, s43
	s_cselect_b32 s4, s5, s4
	s_cselect_b32 s1, s15, s1
	s_add_i32 s5, s4, 1
	s_cmp_ge_u32 s1, s43
	s_cselect_b32 s1, s5, s4
	s_xor_b32 s1, s1, s0
	s_sub_i32 s4, s1, s0
	s_mul_i32 s5, s4, s43
	s_sub_i32 s5, s47, s5
	s_abs_i32 s16, s5
	v_readlane_b32 s17, v219, 46
	s_mul_hi_u32 s17, s16, s17
	v_readlane_b32 s38, v218, 32
	s_mul_i32 s18, s17, s38
	s_sub_i32 s16, s16, s18
	s_ashr_i32 s15, s5, 31
	s_add_i32 s18, s17, 1
	s_sub_i32 s19, s16, s38
	s_cmp_ge_u32 s16, s38
	s_cselect_b32 s17, s18, s17
	s_cselect_b32 s16, s19, s16
	s_add_i32 s18, s17, 1
	s_cmp_ge_u32 s16, s38
	s_cselect_b32 s16, s18, s17
	s_xor_b32 s16, s16, s15
	s_sub_i32 s17, s16, s15
	s_sub_i32 s18, s4, s17
	v_mov_b32_e32 v97, v132
	s_mul_i32 s18, s18, s38
	s_add_i32 s5, s5, s54
	s_add_i32 s48, s5, s18
	v_ashrrev_i32_e32 v0, 7, v97
	v_and_b32_e32 v1, 7, v97
	v_mul_lo_u32 v115, v0, s6
	v_lshrrev_b32_e32 v0, 3, v97
	s_mulk_i32 s48, 0xc0
	s_waitcnt vmcnt(8)
	v_bfe_u32 v109, v97, 5, 1
	v_ashrrev_i32_e32 v8, 3, v97
	v_bitop3_b32 v0, v0, v1, 3 bitop3:0x6c
	v_bfe_u32 v2, v97, 6, 2
	v_xor_b32_e32 v3, v8, v97
	v_xor_b32_e32 v10, v0, v109
	v_add_u32_e32 v0, s48, v8
	s_lshl_b32 s49, s17, 7
	v_bitop3_b32 v2, v3, v2, 7 bitop3:0x6c
	v_ashrrev_i32_e32 v1, 31, v0
	v_readlane_b32 s18, v223, 59
	v_lshlrev_b64 v[0:1], 11, v[0:1]
	v_readlane_b32 s19, v223, 60
	v_lshlrev_b32_e32 v98, 4, v2
	v_add_u32_e32 v2, s49, v8
	v_lshlrev_b32_e32 v120, 4, v97
	v_lshl_add_u64 v[0:1], s[18:19], 0, v[0:1]
	v_ashrrev_i32_e32 v3, 31, v2
	v_readlane_b32 s18, v221, 16
	v_add_u32_e32 v121, 0, v120
	v_mov_b32_e32 v99, v96
	v_lshlrev_b64 v[2:3], 11, v[2:3]
	v_readlane_b32 s19, v221, 17
	v_readfirstlane_b32 s5, v121
	v_add_u32_e32 v122, 0x1000, v121
	v_lshl_add_u64 v[0:1], v[0:1], 0, v[98:99]
	v_lshl_add_u64 v[4:5], s[18:19], 0, v[2:3]
	s_mov_b32 m0, s5
	s_mov_b64 s[18:19], 0x10000
	v_readfirstlane_b32 s5, v122
	v_add_u32_e32 v123, 0x2000, v121
	global_load_lds_dwordx4 v[0:1], off
	v_lshl_add_u64 v[6:7], v[0:1], 0, s[18:19]
	s_mov_b32 m0, s5
	s_mov_b64 s[38:39], 0x20000
	v_readfirstlane_b32 s5, v123
	v_add_u32_e32 v124, 0x3000, v121
	global_load_lds_dwordx4 v[6:7], off
	v_lshl_add_u64 v[6:7], v[0:1], 0, s[38:39]
	s_mov_b32 m0, s5
	s_mov_b64 s[52:53], 0x30000
	v_readfirstlane_b32 s5, v124
	v_add_u32_e32 v125, 0x4000, v121
	global_load_lds_dwordx4 v[6:7], off
	v_lshl_add_u64 v[6:7], v[0:1], 0, s[52:53]
	s_mov_b32 m0, s5
	s_mov_b64 s[72:73], 0x40000
	v_readfirstlane_b32 s5, v125
	v_add_u32_e32 v126, 0x5000, v121
	global_load_lds_dwordx4 v[6:7], off
	v_lshl_add_u64 v[6:7], v[0:1], 0, s[72:73]
	s_mov_b32 m0, s5
	s_mov_b64 s[72:73], 0x50000
	v_readfirstlane_b32 s5, v126
	v_add_u32_e32 v127, 0xc000, v121
	global_load_lds_dwordx4 v[6:7], off
	v_lshl_add_u64 v[0:1], v[0:1], 0, s[72:73]
	s_mov_b32 m0, s5
	v_readfirstlane_b32 s5, v127
	v_add_u32_e32 v128, 0xd000, v121
	global_load_lds_dwordx4 v[0:1], off
	v_lshl_add_u64 v[0:1], v[4:5], 0, v[98:99]
	s_mov_b32 m0, s5
	v_readfirstlane_b32 s5, v128
	v_add_u32_e32 v129, 0xe000, v121
	global_load_lds_dwordx4 v[0:1], off
	v_lshl_add_u64 v[4:5], v[0:1], 0, s[18:19]
	s_mov_b32 m0, s5
	v_readfirstlane_b32 s5, v129
	v_add_u32_e32 v130, 0xf000, v121
	global_load_lds_dwordx4 v[4:5], off
	v_lshl_add_u64 v[4:5], v[0:1], 0, s[38:39]
	s_mov_b32 m0, s5
	v_readfirstlane_b32 s5, v130
	global_load_lds_dwordx4 v[4:5], off
	v_lshl_add_u64 v[0:1], v[0:1], 0, s[52:53]
	s_mov_b32 m0, s5
	s_add_i32 s1, s1, s15
	global_load_lds_dwordx4 v[0:1], off
	s_mul_i32 s4, s20, s4
	s_sub_i32 s1, s1, s4
	s_sub_i32 s1, s1, s16
	s_sub_i32 s0, s1, s0
	v_readlane_b32 s1, v218, 33
	v_lshlrev_b32_e32 v0, 7, v97
	s_mul_i32 s0, s1, s0
	v_and_b32_e32 v0, 0x2f80, v0
	s_add_i32 s0, s0, s46
	v_add_u32_e32 v153, 0, v0
	v_add_u32_e32 v155, s10, v0
	v_add_u32_e32 v0, s0, v8
	v_ashrrev_i32_e32 v1, 31, v0
	v_and_b32_e32 v108, 31, v97
	s_waitcnt vmcnt(0)
	v_lshlrev_b64 v[0:1], 11, v[0:1]
	v_or_b32_e32 v9, v115, v108
	v_lshlrev_b32_e32 v154, 4, v10
	v_lshl_add_u64 v[102:103], s[70:71], 0, v[0:1]
	v_mov_b32_e32 v0, 0
	v_lshl_add_u32 v131, v9, 7, 0
	v_xor_b32_e32 v156, 32, v154
	v_xor_b32_e32 v157, 64, v154
	v_xor_b32_e32 v158, 0x60, v154
	v_lshl_add_u64 v[100:101], s[70:71], 0, v[2:3]
	s_mov_b32 s4, 0
	v_mov_b32_e32 v1, v0
	v_mov_b32_e32 v2, v0
	v_mov_b32_e32 v3, v0
	v_mov_b32_e32 v4, v0
	v_mov_b32_e32 v5, v0
	v_mov_b32_e32 v6, v0
	v_mov_b32_e32 v7, v0
	v_mov_b32_e32 v8, v0
	v_mov_b32_e32 v9, v0
	v_mov_b32_e32 v10, v0
	v_mov_b32_e32 v11, v0
	v_mov_b32_e32 v12, v0
	v_mov_b32_e32 v13, v0
	v_mov_b32_e32 v14, v0
	v_mov_b32_e32 v15, v0
	v_mov_b32_e32 v16, v0
	v_mov_b32_e32 v17, v0
	v_mov_b32_e32 v18, v0
	v_mov_b32_e32 v19, v0
	v_mov_b32_e32 v20, v0
	v_mov_b32_e32 v21, v0
	v_mov_b32_e32 v22, v0
	v_mov_b32_e32 v23, v0
	v_mov_b32_e32 v24, v0
	v_mov_b32_e32 v25, v0
	v_mov_b32_e32 v26, v0
	v_mov_b32_e32 v27, v0
	v_mov_b32_e32 v28, v0
	v_mov_b32_e32 v29, v0
	v_mov_b32_e32 v30, v0
	v_mov_b32_e32 v31, v0
	v_mov_b32_e32 v32, v0
	v_mov_b32_e32 v33, v0
	v_mov_b32_e32 v34, v0
	v_mov_b32_e32 v35, v0
	v_mov_b32_e32 v36, v0
	v_mov_b32_e32 v37, v0
	v_mov_b32_e32 v38, v0
	v_mov_b32_e32 v39, v0
	v_mov_b32_e32 v40, v0
	v_mov_b32_e32 v41, v0
	v_mov_b32_e32 v42, v0
	v_mov_b32_e32 v43, v0
	v_mov_b32_e32 v44, v0
	v_mov_b32_e32 v45, v0
	v_mov_b32_e32 v46, v0
	v_mov_b32_e32 v47, v0
	v_mov_b32_e32 v48, v0
	s_waitcnt vmcnt(0)
; template <int EPI, int MI>
; DI void gemm_tile(const GemmDesc& g, int tm, int tn, char* smem) {
;     ...
;   f32x16 acc[MI][2];
; #pragma unroll
;   for (int a = 0; a < MI; ++a)
; #pragma unroll
;     for (int b = 0; b < 2; ++b)
; #pragma unroll
;       for (int i = 0; i < 16; ++i) acc[a][b][i] = 0.f;
;   const int srow = tid >> 3;
;   const int schunk = (tid & 7) ^ ((srow & 7) ^ ((srow >> 3) & 3));
;     ...
;   const int rowA = wm * (32 * MI) + r, rowB = wn * 64 + r;
;   const int hk = hh ^ ((r & 7) ^ ((r >> 3) & 3));
;     ...
;   G_GLDS(0, 0);
;   asm volatile("s_waitcnt vmcnt(0)" ::: "memory");
;   __syncthreads();
;   for (int kt = 0; kt < nk; kt += 2) {
;     if (kt + 1 < nk) G_GLDS(kt + 1, 1);
;     G_COMPUTE(0);
;     asm volatile("s_waitcnt vmcnt(0)" ::: "memory");
	v_mov_b32_e32 v49, v0
	v_mov_b32_e32 v50, v0
	v_mov_b32_e32 v51, v0
	v_mov_b32_e32 v52, v0
	v_mov_b32_e32 v53, v0
	v_mov_b32_e32 v54, v0
	v_mov_b32_e32 v55, v0
	v_mov_b32_e32 v56, v0
	v_mov_b32_e32 v57, v0
	v_mov_b32_e32 v58, v0
	v_mov_b32_e32 v59, v0
	v_mov_b32_e32 v60, v0
	v_mov_b32_e32 v61, v0
	v_mov_b32_e32 v62, v0
	v_mov_b32_e32 v63, v0
	v_mov_b32_e32 v64, v0
	v_mov_b32_e32 v65, v0
	v_mov_b32_e32 v66, v0
	v_mov_b32_e32 v67, v0
	v_mov_b32_e32 v68, v0
	v_mov_b32_e32 v69, v0
	v_mov_b32_e32 v70, v0
	v_mov_b32_e32 v71, v0
	v_mov_b32_e32 v72, v0
	v_mov_b32_e32 v73, v0
	v_mov_b32_e32 v74, v0
	v_mov_b32_e32 v75, v0
	v_mov_b32_e32 v76, v0
	v_mov_b32_e32 v77, v0
	v_mov_b32_e32 v78, v0
	v_mov_b32_e32 v79, v0
	v_mov_b32_e32 v80, v0
	v_mov_b32_e32 v81, v0
	v_mov_b32_e32 v82, v0
	v_mov_b32_e32 v83, v0
	v_mov_b32_e32 v84, v0
	v_mov_b32_e32 v85, v0
	v_mov_b32_e32 v86, v0
	v_mov_b32_e32 v87, v0
	v_mov_b32_e32 v88, v0
	v_mov_b32_e32 v89, v0
	v_mov_b32_e32 v90, v0
	v_mov_b32_e32 v91, v0
	v_mov_b32_e32 v92, v0
	v_mov_b32_e32 v93, v0
	v_mov_b32_e32 v94, v0
	v_mov_b32_e32 v95, v0
	v_add_u32_e32 v162, v131, v154
	v_add_u32_e32 v163, v131, v156
	v_add_u32_e32 v164, v131, v157
	v_add_u32_e32 v165, v131, v158
	v_add_u32_e32 v166, v153, v154
	v_add_u32_e32 v167, v153, v156
	v_add_u32_e32 v168, v153, v157
	v_add_u32_e32 v169, v153, v158
	v_add_u32_e32 v170, v155, v154
	v_add_u32_e32 v171, v155, v156
	v_add_u32_e32 v172, v155, v157
	v_add_u32_e32 v173, v155, v158
	v_lshl_add_u64 v[252:253], v[102:103], 0, v[98:99]
	v_lshl_add_u64 v[254:255], v[100:101], 0, v[98:99]
	v_readfirstlane_b32 s100, v121
	s_mov_b64 s[0:1], 0x80
	s_waitcnt vmcnt(0) lgkmcnt(0)
	s_barrier
	s_add_u32 m0, s100, 0x6000
	v_lshl_add_u64 v[106:107], v[252:253], 0, s[96:97]
	global_load_lds_dwordx4 v[106:107], off
	s_add_u32 m0, s100, 0x7000
	v_lshl_add_u64 v[106:107], v[252:253], 0, s[50:51]
	global_load_lds_dwordx4 v[106:107], off
	s_add_u32 m0, s100, 0x8000
	v_lshl_add_u64 v[106:107], v[252:253], 0, s[24:25]
	global_load_lds_dwordx4 v[106:107], off
	s_add_u32 m0, s100, 0x9000
	v_lshl_add_u64 v[106:107], v[252:253], 0, s[26:27]
	global_load_lds_dwordx4 v[106:107], off
	s_add_u32 m0, s100, 0xa000
	v_lshl_add_u64 v[106:107], v[252:253], 0, s[28:29]
	global_load_lds_dwordx4 v[106:107], off
	s_add_u32 m0, s100, 0xb000
	v_lshl_add_u64 v[106:107], v[252:253], 0, s[30:31]
	global_load_lds_dwordx4 v[106:107], off
	v_lshl_add_u64 v[252:253], v[252:253], 0, s[0:1]
	s_mov_b64 s[16:17], 0x2100080
	s_add_u32 m0, s100, 0x10000
	v_lshl_add_u64 v[106:107], v[254:255], 0, s[16:17]
	global_load_lds_dwordx4 v[106:107], off
	s_mov_b64 s[16:17], 0x2110080
	s_add_u32 m0, s100, 0x11000
	v_lshl_add_u64 v[106:107], v[254:255], 0, s[16:17]
	global_load_lds_dwordx4 v[106:107], off
	s_mov_b64 s[16:17], 0x2120080
	s_add_u32 m0, s100, 0x12000
	v_lshl_add_u64 v[106:107], v[254:255], 0, s[16:17]
	global_load_lds_dwordx4 v[106:107], off
	s_mov_b64 s[16:17], 0x2130080
	s_add_u32 m0, s100, 0x13000
	v_lshl_add_u64 v[106:107], v[254:255], 0, s[16:17]
	global_load_lds_dwordx4 v[106:107], off
	v_lshl_add_u64 v[254:255], v[254:255], 0, s[0:1]
	ds_read_b128 v[236:239], v166 offset:49152
	ds_read_b128 v[240:243], v166 offset:53248
	ds_read_b128 v[224:227], v162
	ds_read_b128 v[228:231], v162 offset:4096
	s_mov_b32 s101, 0
.Lgw_loop:
	ds_read_b128 v[232:235], v162 offset:8192
	s_waitcnt lgkmcnt(2)
	v_mfma_f32_32x32x16_bf16 v[80:95], v[224:227], v[236:239], v[80:95]
	v_mfma_f32_32x32x16_bf16 v[64:79], v[224:227], v[240:243], v[64:79]
	ds_read_b128 v[244:247], v167 offset:49152
	ds_read_b128 v[248:251], v167 offset:53248
	ds_read_b128 v[224:227], v163
	s_waitcnt lgkmcnt(4)
	v_mfma_f32_32x32x16_bf16 v[48:63], v[228:231], v[236:239], v[48:63]
	v_mfma_f32_32x32x16_bf16 v[32:47], v[228:231], v[240:243], v[32:47]
	ds_read_b128 v[228:231], v163 offset:4096
	s_waitcnt lgkmcnt(4)
	v_mfma_f32_32x32x16_bf16 v[16:31], v[232:235], v[236:239], v[16:31]
	v_mfma_f32_32x32x16_bf16 v[0:15], v[232:235], v[240:243], v[0:15]
	ds_read_b128 v[232:235], v163 offset:8192
	s_waitcnt lgkmcnt(2)
	v_mfma_f32_32x32x16_bf16 v[80:95], v[224:227], v[244:247], v[80:95]
	v_mfma_f32_32x32x16_bf16 v[64:79], v[224:227], v[248:251], v[64:79]
	ds_read_b128 v[236:239], v168 offset:49152
	ds_read_b128 v[240:243], v168 offset:53248
	ds_read_b128 v[224:227], v164
	s_waitcnt lgkmcnt(4)
	v_mfma_f32_32x32x16_bf16 v[48:63], v[228:231], v[244:247], v[48:63]
	v_mfma_f32_32x32x16_bf16 v[32:47], v[228:231], v[248:251], v[32:47]
	ds_read_b128 v[228:231], v164 offset:4096
	s_waitcnt lgkmcnt(4)
	v_mfma_f32_32x32x16_bf16 v[16:31], v[232:235], v[244:247], v[16:31]
	v_mfma_f32_32x32x16_bf16 v[0:15], v[232:235], v[248:251], v[0:15]
	ds_read_b128 v[232:235], v164 offset:8192
	s_waitcnt lgkmcnt(2)
	v_mfma_f32_32x32x16_bf16 v[80:95], v[224:227], v[236:239], v[80:95]
	v_mfma_f32_32x32x16_bf16 v[64:79], v[224:227], v[240:243], v[64:79]
	ds_read_b128 v[244:247], v169 offset:49152
	ds_read_b128 v[248:251], v169 offset:53248
	ds_read_b128 v[224:227], v165
	s_waitcnt lgkmcnt(4)
	v_mfma_f32_32x32x16_bf16 v[48:63], v[228:231], v[236:239], v[48:63]
	v_mfma_f32_32x32x16_bf16 v[32:47], v[228:231], v[240:243], v[32:47]
	ds_read_b128 v[228:231], v165 offset:4096
	s_waitcnt lgkmcnt(4)
	v_mfma_f32_32x32x16_bf16 v[16:31], v[232:235], v[236:239], v[16:31]
	v_mfma_f32_32x32x16_bf16 v[0:15], v[232:235], v[240:243], v[0:15]
	ds_read_b128 v[232:235], v165 offset:8192
	s_waitcnt lgkmcnt(2)
	v_mfma_f32_32x32x16_bf16 v[80:95], v[224:227], v[244:247], v[80:95]
	v_mfma_f32_32x32x16_bf16 v[64:79], v[224:227], v[248:251], v[64:79]
	s_waitcnt lgkmcnt(0)
	s_waitcnt vmcnt(0)
	s_barrier
	s_cmp_eq_u32 s101, 14
	s_cbranch_scc1 .Lgw_noearly
; template <int EPI, int MI>
; DI void gemm_tile(const GemmDesc& g, int tm, int tn, char* smem) {
;     ...
;   for (int kt = 0; kt < nk; kt += 2) {
;     if (kt + 1 < nk) G_GLDS(kt + 1, 1);
;     G_COMPUTE(0);
;     asm volatile("s_waitcnt vmcnt(0)" ::: "memory");
;     __syncthreads();
;     if (kt + 1 < nk) {
;       if (kt + 2 < nk) G_GLDS(kt + 2, 0);
;       G_COMPUTE(1);
;       asm volatile("s_waitcnt vmcnt(0)" ::: "memory");
;       __syncthreads();
;     }
	s_mov_b32 m0, s100
	v_lshl_add_u64 v[106:107], v[252:253], 0, s[96:97]
	global_load_lds_dwordx4 v[106:107], off
	s_add_u32 m0, s100, 0x1000
	v_lshl_add_u64 v[106:107], v[252:253], 0, s[50:51]
	global_load_lds_dwordx4 v[106:107], off
	s_add_u32 m0, s100, 0x2000
	v_lshl_add_u64 v[106:107], v[252:253], 0, s[24:25]
	global_load_lds_dwordx4 v[106:107], off
	s_add_u32 m0, s100, 0x3000
	v_lshl_add_u64 v[106:107], v[252:253], 0, s[26:27]
	global_load_lds_dwordx4 v[106:107], off
	s_add_u32 m0, s100, 0x4000
	v_lshl_add_u64 v[106:107], v[252:253], 0, s[28:29]
	global_load_lds_dwordx4 v[106:107], off
	s_add_u32 m0, s100, 0x5000
	v_lshl_add_u64 v[106:107], v[252:253], 0, s[30:31]
	global_load_lds_dwordx4 v[106:107], off
	v_lshl_add_u64 v[252:253], v[252:253], 0, s[0:1]
	s_mov_b64 s[16:17], 0x2100080
	s_add_u32 m0, s100, 0xc000
	v_lshl_add_u64 v[106:107], v[254:255], 0, s[16:17]
	global_load_lds_dwordx4 v[106:107], off
	s_mov_b64 s[16:17], 0x2110080
	s_add_u32 m0, s100, 0xd000
	v_lshl_add_u64 v[106:107], v[254:255], 0, s[16:17]
	global_load_lds_dwordx4 v[106:107], off
	s_mov_b64 s[16:17], 0x2120080
	s_add_u32 m0, s100, 0xe000
	v_lshl_add_u64 v[106:107], v[254:255], 0, s[16:17]
	global_load_lds_dwordx4 v[106:107], off
	s_mov_b64 s[16:17], 0x2130080
	s_add_u32 m0, s100, 0xf000
	v_lshl_add_u64 v[106:107], v[254:255], 0, s[16:17]
	global_load_lds_dwordx4 v[106:107], off
	v_lshl_add_u64 v[254:255], v[254:255], 0, s[0:1]
.Lgw_noearly:
	ds_read_b128 v[236:239], v170
	ds_read_b128 v[240:243], v170 offset:4096
	ds_read_b128 v[224:227], v162 offset:24576
	v_mfma_f32_32x32x16_bf16 v[48:63], v[228:231], v[244:247], v[48:63]
	v_mfma_f32_32x32x16_bf16 v[32:47], v[228:231], v[248:251], v[32:47]
	ds_read_b128 v[228:231], v162 offset:28672
	v_mfma_f32_32x32x16_bf16 v[16:31], v[232:235], v[244:247], v[16:31]
	v_mfma_f32_32x32x16_bf16 v[0:15], v[232:235], v[248:251], v[0:15]
	s_cmp_eq_u32 s101, 14
	s_cbranch_scc1 .Lgw_last
	ds_read_b128 v[232:235], v162 offset:32768
	s_waitcnt lgkmcnt(2)
	v_mfma_f32_32x32x16_bf16 v[80:95], v[224:227], v[236:239], v[80:95]
	v_mfma_f32_32x32x16_bf16 v[64:79], v[224:227], v[240:243], v[64:79]
	ds_read_b128 v[244:247], v171
	ds_read_b128 v[248:251], v171 offset:4096
	ds_read_b128 v[224:227], v163 offset:24576
	s_waitcnt lgkmcnt(4)
	v_mfma_f32_32x32x16_bf16 v[48:63], v[228:231], v[236:239], v[48:63]
	v_mfma_f32_32x32x16_bf16 v[32:47], v[228:231], v[240:243], v[32:47]
	ds_read_b128 v[228:231], v163 offset:28672
	s_waitcnt lgkmcnt(4)
	v_mfma_f32_32x32x16_bf16 v[16:31], v[232:235], v[236:239], v[16:31]
	v_mfma_f32_32x32x16_bf16 v[0:15], v[232:235], v[240:243], v[0:15]
	ds_read_b128 v[232:235], v163 offset:32768
	s_waitcnt lgkmcnt(2)
	v_mfma_f32_32x32x16_bf16 v[80:95], v[224:227], v[244:247], v[80:95]
	v_mfma_f32_32x32x16_bf16 v[64:79], v[224:227], v[248:251], v[64:79]
	ds_read_b128 v[236:239], v172
	ds_read_b128 v[240:243], v172 offset:4096
	ds_read_b128 v[224:227], v164 offset:24576
	s_waitcnt lgkmcnt(4)
	v_mfma_f32_32x32x16_bf16 v[48:63], v[228:231], v[244:247], v[48:63]
	v_mfma_f32_32x32x16_bf16 v[32:47], v[228:231], v[248:251], v[32:47]
	ds_read_b128 v[228:231], v164 offset:28672
	s_waitcnt lgkmcnt(4)
	v_mfma_f32_32x32x16_bf16 v[16:31], v[232:235], v[244:247], v[16:31]
	v_mfma_f32_32x32x16_bf16 v[0:15], v[232:235], v[248:251], v[0:15]
	ds_read_b128 v[232:235], v164 offset:32768
	s_waitcnt lgkmcnt(2)
	v_mfma_f32_32x32x16_bf16 v[80:95], v[224:227], v[236:239], v[80:95]
	v_mfma_f32_32x32x16_bf16 v[64:79], v[224:227], v[240:243], v[64:79]
	ds_read_b128 v[244:247], v173
	ds_read_b128 v[248:251], v173 offset:4096
	ds_read_b128 v[224:227], v165 offset:24576
	s_waitcnt lgkmcnt(4)
	v_mfma_f32_32x32x16_bf16 v[48:63], v[228:231], v[236:239], v[48:63]
	v_mfma_f32_32x32x16_bf16 v[32:47], v[228:231], v[240:243], v[32:47]
	ds_read_b128 v[228:231], v165 offset:28672
	s_waitcnt lgkmcnt(4)
	v_mfma_f32_32x32x16_bf16 v[16:31], v[232:235], v[236:239], v[16:31]
	v_mfma_f32_32x32x16_bf16 v[0:15], v[232:235], v[240:243], v[0:15]
	ds_read_b128 v[232:235], v165 offset:32768
	s_waitcnt lgkmcnt(2)
	v_mfma_f32_32x32x16_bf16 v[80:95], v[224:227], v[244:247], v[80:95]
	v_mfma_f32_32x32x16_bf16 v[64:79], v[224:227], v[248:251], v[64:79]
	s_waitcnt lgkmcnt(0)
	s_waitcnt vmcnt(0)
	s_barrier
	s_add_u32 m0, s100, 0x6000
	v_lshl_add_u64 v[106:107], v[252:253], 0, s[96:97]
	global_load_lds_dwordx4 v[106:107], off
	s_add_u32 m0, s100, 0x7000
	v_lshl_add_u64 v[106:107], v[252:253], 0, s[50:51]
	global_load_lds_dwordx4 v[106:107], off
	s_add_u32 m0, s100, 0x8000
	v_lshl_add_u64 v[106:107], v[252:253], 0, s[24:25]
	global_load_lds_dwordx4 v[106:107], off
	s_add_u32 m0, s100, 0x9000
	v_lshl_add_u64 v[106:107], v[252:253], 0, s[26:27]
	global_load_lds_dwordx4 v[106:107], off
	s_add_u32 m0, s100, 0xa000
	v_lshl_add_u64 v[106:107], v[252:253], 0, s[28:29]
	global_load_lds_dwordx4 v[106:107], off
	s_add_u32 m0, s100, 0xb000
	v_lshl_add_u64 v[106:107], v[252:253], 0, s[30:31]
	global_load_lds_dwordx4 v[106:107], off
	v_lshl_add_u64 v[252:253], v[252:253], 0, s[0:1]
	s_mov_b64 s[16:17], 0x2100080
	s_add_u32 m0, s100, 0x10000
	v_lshl_add_u64 v[106:107], v[254:255], 0, s[16:17]
	global_load_lds_dwordx4 v[106:107], off
	s_mov_b64 s[16:17], 0x2110080
	s_add_u32 m0, s100, 0x11000
	v_lshl_add_u64 v[106:107], v[254:255], 0, s[16:17]
	global_load_lds_dwordx4 v[106:107], off
	s_mov_b64 s[16:17], 0x2120080
	s_add_u32 m0, s100, 0x12000
	v_lshl_add_u64 v[106:107], v[254:255], 0, s[16:17]
	global_load_lds_dwordx4 v[106:107], off
	s_mov_b64 s[16:17], 0x2130080
	s_add_u32 m0, s100, 0x13000
	v_lshl_add_u64 v[106:107], v[254:255], 0, s[16:17]
	global_load_lds_dwordx4 v[106:107], off
	v_lshl_add_u64 v[254:255], v[254:255], 0, s[0:1]
	ds_read_b128 v[236:239], v166 offset:49152
	ds_read_b128 v[240:243], v166 offset:53248
	ds_read_b128 v[224:227], v162
	v_mfma_f32_32x32x16_bf16 v[48:63], v[228:231], v[244:247], v[48:63]
	v_mfma_f32_32x32x16_bf16 v[32:47], v[228:231], v[248:251], v[32:47]
	ds_read_b128 v[228:231], v162 offset:4096
	v_mfma_f32_32x32x16_bf16 v[16:31], v[232:235], v[244:247], v[16:31]
	v_mfma_f32_32x32x16_bf16 v[0:15], v[232:235], v[248:251], v[0:15]
	s_add_u32 s101, s101, 2
	s_branch .Lgw_loop

; template <int EPI, int MI>
; DI void gemm_tile(const GemmDesc& g, int tm, int tn, char* smem) {
;     ...
;   const int tid = get_tid(), lane = tid & 63, wave = tid >> 6, r = lane & 31, hh = lane >> 5;
;   const int wm = wave >> 1, wn = wave & 1;
;   const int m0 = tm * BM, n0 = tn * 128;
;   const int nk = g.K >> 6;
;   f32x16 acc[MI][2];
; #pragma unroll
;   for (int a = 0; a < MI; ++a)
; #pragma unroll
;     for (int b = 0; b < 2; ++b)
; #pragma unroll
;       for (int i = 0; i < 16; ++i) acc[a][b][i] = 0.f;
;   const int srow = tid >> 3;
;   const int schunk = (tid & 7) ^ ((srow & 7) ^ ((srow >> 3) & 3));
;     ...
;   const int rowA = wm * (32 * MI) + r, rowB = wn * 64 + r;
;   const int hk = hh ^ ((r & 7) ^ ((r >> 3) & 3));
;     ...
;   G_GLDS(0, 0);
;   asm volatile("s_waitcnt vmcnt(0)" ::: "memory");
;   __syncthreads();
; template <int EPI, int MI>
; DI void gemm_phase(const GemmDesc& g, char* smem, int vb, int nvb) {
;     ...
;   for (int q = start; q < local; q += step) {
;     const int mg = q / per;
;     const int rem = q - mg * per;
;     const int tn = rem / PM;
;     const int tm = mbase + mg * PM + (rem - tn * PM);
;     gemm_tile<EPI, MI>(g, tm, tn, smem);
.LBB0_1410:
	s_abs_i32 s1, s39
	s_mul_hi_u32 s40, s1, s17
	s_mul_i32 s41, s40, s15
	s_sub_i32 s1, s1, s41
	s_ashr_i32 s0, s39, 31
	s_add_i32 s41, s40, 1
	s_sub_i32 s42, s1, s15
	s_cmp_ge_u32 s1, s15
	s_cselect_b32 s40, s41, s40
	s_cselect_b32 s1, s42, s1
	s_add_i32 s41, s40, 1
	s_cmp_ge_u32 s1, s15
	s_cselect_b32 s1, s41, s40
	s_xor_b32 s1, s1, s0
	s_sub_i32 s40, s1, s0
	s_mul_i32 s41, s40, s15
	s_sub_i32 s42, s39, s41
	s_abs_i32 s41, s42
	s_mul_hi_u32 s44, s41, s18
	s_mul_i32 s45, s44, s4
	s_sub_i32 s41, s41, s45
	s_ashr_i32 s43, s42, 31
	s_add_i32 s45, s44, 1
	s_sub_i32 s46, s41, s4
	s_cmp_ge_u32 s41, s4
	s_cselect_b32 s44, s45, s44
	s_cselect_b32 s41, s46, s41
	s_add_i32 s45, s44, 1
	s_cmp_ge_u32 s41, s4
	s_cselect_b32 s41, s45, s44
	s_xor_b32 s44, s41, s43
	s_sub_i32 s41, s44, s43
	s_sub_i32 s40, s40, s41
	v_mov_b32_e32 v6, v132
	s_mul_i32 s40, s40, s4
	s_add_i32 s42, s42, s16
	s_add_i32 s42, s42, s40
	v_ashrrev_i32_e32 v76, 3, v6
	v_bfe_u32 v0, v6, 6, 2
	v_xor_b32_e32 v1, v76, v6
	s_lshl_b32 s40, s42, 7
	v_bitop3_b32 v2, v1, v0, 7 bitop3:0x6c
	v_ashrrev_i32_e32 v0, 1, v6
	v_and_b32_e32 v77, 7, v6
	v_and_b32_e32 v79, 0xffffffc0, v0
	v_lshrrev_b32_e32 v0, 3, v6
	v_add_u32_e32 v64, s40, v76
	v_bfe_u32 v78, v6, 5, 1
	v_bitop3_b32 v0, v0, v77, 3 bitop3:0x6c
	v_ashrrev_i32_e32 v65, 31, v64
	v_readlane_b32 s46, v223, 59
	v_and_b32_e32 v80, 31, v6
	v_bfe_u32 v81, v6, 6, 1
	v_xor_b32_e32 v9, v0, v78
	v_lshlrev_b64 v[0:1], 11, v[64:65]
	v_readlane_b32 s47, v223, 60
	v_lshlrev_b32_e32 v66, 4, v2
	v_lshl_add_u32 v2, s41, 7, v76
	v_lshlrev_b32_e32 v6, 4, v6
	v_lshl_add_u64 v[0:1], s[46:47], 0, v[0:1]
	v_ashrrev_i32_e32 v3, 31, v2
	v_readlane_b32 s46, v220, 54
	v_add_u32_e32 v65, 0, v6
	v_mov_b32_e32 v67, v96
	v_lshlrev_b64 v[2:3], 11, v[2:3]
	v_readlane_b32 s47, v220, 55
	v_readfirstlane_b32 s42, v65
	v_add_u32_e32 v82, 0x1000, v65
	v_lshl_add_u64 v[0:1], v[0:1], 0, v[66:67]
	v_lshl_add_u64 v[4:5], s[46:47], 0, v[2:3]
	s_mov_b32 m0, s42
	s_mov_b64 s[46:47], 0x10000
	v_readfirstlane_b32 s42, v82
	v_add_u32_e32 v83, 0x2000, v65
	global_load_lds_dwordx4 v[0:1], off
	v_lshl_add_u64 v[6:7], v[0:1], 0, s[46:47]
	s_mov_b32 m0, s42
	s_mov_b64 s[52:53], 0x20000
	v_readfirstlane_b32 s42, v83
	v_add_u32_e32 v84, 0x3000, v65
	global_load_lds_dwordx4 v[6:7], off
	v_lshl_add_u64 v[6:7], v[0:1], 0, s[52:53]
	s_mov_b32 m0, s42
	s_mov_b64 s[72:73], 0x30000
	v_readfirstlane_b32 s42, v84
	v_add_u32_e32 v85, 0x8000, v65
	global_load_lds_dwordx4 v[6:7], off
	v_lshl_add_u64 v[0:1], v[0:1], 0, s[72:73]
	s_mov_b32 m0, s42
	v_readfirstlane_b32 s42, v85
	v_add_u32_e32 v86, 0x9000, v65
	global_load_lds_dwordx4 v[0:1], off
	v_lshl_add_u64 v[0:1], v[4:5], 0, v[66:67]
	s_mov_b32 m0, s42
	v_readfirstlane_b32 s42, v86
	v_add_u32_e32 v87, 0xa000, v65
	global_load_lds_dwordx4 v[0:1], off
	v_lshl_add_u64 v[4:5], v[0:1], 0, s[46:47]
	s_mov_b32 m0, s42
	v_readfirstlane_b32 s42, v87
	v_add_u32_e32 v88, 0xb000, v65
	global_load_lds_dwordx4 v[4:5], off
	v_lshl_add_u64 v[4:5], v[0:1], 0, s[52:53]
	s_mov_b32 m0, s42
	v_readfirstlane_b32 s42, v88
	global_load_lds_dwordx4 v[4:5], off
	v_lshl_add_u64 v[0:1], v[0:1], 0, s[72:73]
	s_mov_b32 m0, s42
	s_mul_i32 s0, s0, 43
	global_load_lds_dwordx4 v[0:1], off
	s_add_i32 s43, s43, s0
	s_sub_i32 s0, s43, s44
	s_mul_i32 s1, s1, 43
	s_sub_i32 s0, s0, s1
	v_lshlrev_b32_e32 v0, 7, v80
	s_mul_i32 s0, s38, s0
	v_lshl_or_b32 v0, v81, 13, v0
	s_add_i32 s0, s0, s19
	v_add_u32_e32 v90, 0, v0
	v_add_u32_e32 v0, s0, v76
	v_ashrrev_i32_e32 v1, 31, v0
	s_waitcnt vmcnt(0)
	v_lshlrev_b64 v[0:1], 11, v[0:1]
	v_or_b32_e32 v8, v79, v80
	v_lshlrev_b32_e32 v91, 4, v9
	v_lshl_add_u64 v[68:69], s[70:71], 0, v[0:1]
	v_mov_b32_e32 v0, 0
	v_lshl_add_u32 v89, v8, 7, 0
	v_xor_b32_e32 v92, 32, v91
	v_xor_b32_e32 v93, 64, v91
	v_xor_b32_e32 v94, 0x60, v91
	v_lshl_add_u64 v[70:71], s[70:71], 0, v[2:3]
	s_mov_b32 s42, 0
	v_mov_b32_e32 v1, v0
	v_mov_b32_e32 v2, v0
	v_mov_b32_e32 v3, v0
	v_mov_b32_e32 v4, v0
	v_mov_b32_e32 v5, v0
	v_mov_b32_e32 v6, v0
	v_mov_b32_e32 v7, v0
	v_mov_b32_e32 v8, v0
	v_mov_b32_e32 v9, v0
	v_mov_b32_e32 v10, v0
	v_mov_b32_e32 v11, v0
	v_mov_b32_e32 v12, v0
	v_mov_b32_e32 v13, v0
	v_mov_b32_e32 v14, v0
	v_mov_b32_e32 v15, v0
	v_mov_b32_e32 v16, v0
	v_mov_b32_e32 v17, v0
	v_mov_b32_e32 v18, v0
	v_mov_b32_e32 v19, v0
	v_mov_b32_e32 v20, v0
	v_mov_b32_e32 v21, v0
	v_mov_b32_e32 v22, v0
	v_mov_b32_e32 v23, v0
	v_mov_b32_e32 v24, v0
	v_mov_b32_e32 v25, v0
	v_mov_b32_e32 v26, v0
	v_mov_b32_e32 v27, v0
	v_mov_b32_e32 v28, v0
	v_mov_b32_e32 v29, v0
	v_mov_b32_e32 v30, v0
	v_mov_b32_e32 v31, v0
	v_mov_b32_e32 v32, v0
	v_mov_b32_e32 v33, v0
	v_mov_b32_e32 v34, v0
	v_mov_b32_e32 v35, v0
	v_mov_b32_e32 v36, v0
	v_mov_b32_e32 v37, v0
	v_mov_b32_e32 v38, v0
	v_mov_b32_e32 v39, v0
	v_mov_b32_e32 v40, v0
	v_mov_b32_e32 v41, v0
	v_mov_b32_e32 v42, v0
	v_mov_b32_e32 v43, v0
	v_mov_b32_e32 v44, v0
	v_mov_b32_e32 v45, v0
	v_mov_b32_e32 v46, v0
	v_mov_b32_e32 v47, v0
	v_mov_b32_e32 v48, v0
	v_mov_b32_e32 v49, v0
	v_mov_b32_e32 v50, v0
	v_mov_b32_e32 v51, v0
	v_mov_b32_e32 v52, v0
	v_mov_b32_e32 v53, v0
	v_mov_b32_e32 v54, v0
	v_mov_b32_e32 v55, v0
	v_mov_b32_e32 v56, v0
	v_mov_b32_e32 v57, v0
	v_mov_b32_e32 v58, v0
	v_mov_b32_e32 v59, v0
	v_mov_b32_e32 v60, v0
	v_mov_b32_e32 v61, v0
	v_mov_b32_e32 v62, v0
	v_mov_b32_e32 v63, v0
	v_add_u32_e32 v98, v89, v91
	v_add_u32_e32 v99, v89, v92
	v_add_u32_e32 v100, v89, v93
	v_add_u32_e32 v101, v89, v94
	v_add_u32_e32 v102, v90, v91
	v_add_u32_e32 v103, v90, v92
	v_add_u32_e32 v104, v90, v93
	v_add_u32_e32 v105, v90, v94
	v_lshl_add_u64 v[72:73], v[68:69], 0, v[66:67]
	v_lshl_add_u64 v[74:75], v[70:71], 0, v[66:67]
	v_readfirstlane_b32 s100, v65
	s_mov_b64 s[44:45], 0x80
	s_waitcnt vmcnt(0) lgkmcnt(0)
	s_barrier
; template <int EPI, int MI>
; DI void gemm_tile(const GemmDesc& g, int tm, int tn, char* smem) {
;     ...
;   G_GLDS(0, 0);
;   asm volatile("s_waitcnt vmcnt(0)" ::: "memory");
;   __syncthreads();
;   for (int kt = 0; kt < nk; kt += 2) {
;     if (kt + 1 < nk) G_GLDS(kt + 1, 1);
;     G_COMPUTE(0);
;     asm volatile("s_waitcnt vmcnt(0)" ::: "memory");
;     __syncthreads();
;     if (kt + 1 < nk) {
;       if (kt + 2 < nk) G_GLDS(kt + 2, 0);
;       G_COMPUTE(1);
;       asm volatile("s_waitcnt vmcnt(0)" ::: "memory");
;       __syncthreads();
;     }
	s_add_u32 m0, s100, 0x4000
	v_lshl_add_u64 v[106:107], v[72:73], 0, s[96:97]
	global_load_lds_dwordx4 v[106:107], off
	s_add_u32 m0, s100, 0x5000
	v_lshl_add_u64 v[106:107], v[72:73], 0, s[50:51]
	global_load_lds_dwordx4 v[106:107], off
	s_add_u32 m0, s100, 0x6000
	v_lshl_add_u64 v[106:107], v[72:73], 0, s[24:25]
	global_load_lds_dwordx4 v[106:107], off
	s_add_u32 m0, s100, 0x7000
	v_lshl_add_u64 v[106:107], v[72:73], 0, s[26:27]
	global_load_lds_dwordx4 v[106:107], off
	v_lshl_add_u64 v[72:73], v[72:73], 0, s[44:45]
	s_mov_b64 s[0:1], 0xb00080
	s_add_u32 m0, s100, 0xc000
	v_lshl_add_u64 v[106:107], v[74:75], 0, s[0:1]
	global_load_lds_dwordx4 v[106:107], off
	s_mov_b64 s[0:1], 0xb10080
	s_add_u32 m0, s100, 0xd000
	v_lshl_add_u64 v[106:107], v[74:75], 0, s[0:1]
	global_load_lds_dwordx4 v[106:107], off
	s_mov_b64 s[0:1], 0xb20080
	s_add_u32 m0, s100, 0xe000
	v_lshl_add_u64 v[106:107], v[74:75], 0, s[0:1]
	global_load_lds_dwordx4 v[106:107], off
	s_mov_b64 s[0:1], 0xb30080
	s_add_u32 m0, s100, 0xf000
	v_lshl_add_u64 v[106:107], v[74:75], 0, s[0:1]
	global_load_lds_dwordx4 v[106:107], off
	v_lshl_add_u64 v[74:75], v[74:75], 0, s[44:45]
	ds_read_b128 v[240:243], v102 offset:32768
	ds_read_b128 v[244:247], v102 offset:36864
	ds_read_b128 v[224:227], v98
	ds_read_b128 v[228:231], v98 offset:4096
	s_mov_b32 s101, 0
.Lgc_loop:
	ds_read_b128 v[248:251], v103 offset:32768
	ds_read_b128 v[252:255], v103 offset:36864
	ds_read_b128 v[232:235], v99
	s_waitcnt lgkmcnt(4)
	v_mfma_f32_32x32x16_bf16 v[48:63], v[224:227], v[240:243], v[48:63]
	v_mfma_f32_32x32x16_bf16 v[32:47], v[224:227], v[244:247], v[32:47]
	ds_read_b128 v[236:239], v99 offset:4096
	s_waitcnt lgkmcnt(4)
	v_mfma_f32_32x32x16_bf16 v[16:31], v[228:231], v[240:243], v[16:31]
	v_mfma_f32_32x32x16_bf16 v[0:15], v[228:231], v[244:247], v[0:15]
	ds_read_b128 v[240:243], v104 offset:32768
	ds_read_b128 v[244:247], v104 offset:36864
	ds_read_b128 v[224:227], v100
	s_waitcnt lgkmcnt(4)
	v_mfma_f32_32x32x16_bf16 v[48:63], v[232:235], v[248:251], v[48:63]
	v_mfma_f32_32x32x16_bf16 v[32:47], v[232:235], v[252:255], v[32:47]
	ds_read_b128 v[228:231], v100 offset:4096
	s_waitcnt lgkmcnt(4)
	v_mfma_f32_32x32x16_bf16 v[16:31], v[236:239], v[248:251], v[16:31]
	v_mfma_f32_32x32x16_bf16 v[0:15], v[236:239], v[252:255], v[0:15]
	ds_read_b128 v[248:251], v105 offset:32768
	ds_read_b128 v[252:255], v105 offset:36864
	ds_read_b128 v[232:235], v101
	s_waitcnt lgkmcnt(4)
	v_mfma_f32_32x32x16_bf16 v[48:63], v[224:227], v[240:243], v[48:63]
	v_mfma_f32_32x32x16_bf16 v[32:47], v[224:227], v[244:247], v[32:47]
	ds_read_b128 v[236:239], v101 offset:4096
	s_waitcnt lgkmcnt(4)
	v_mfma_f32_32x32x16_bf16 v[16:31], v[228:231], v[240:243], v[16:31]
	v_mfma_f32_32x32x16_bf16 v[0:15], v[228:231], v[244:247], v[0:15]
	s_waitcnt lgkmcnt(0)
	s_waitcnt vmcnt(0)
	s_barrier
	s_cmp_eq_u32 s101, 14
	s_cbranch_scc1 .Lgc_noearly
	s_mov_b32 m0, s100
	v_lshl_add_u64 v[106:107], v[72:73], 0, s[96:97]
	global_load_lds_dwordx4 v[106:107], off
	s_add_u32 m0, s100, 0x1000
	v_lshl_add_u64 v[106:107], v[72:73], 0, s[50:51]
	global_load_lds_dwordx4 v[106:107], off
	s_add_u32 m0, s100, 0x2000
	v_lshl_add_u64 v[106:107], v[72:73], 0, s[24:25]
	global_load_lds_dwordx4 v[106:107], off
	s_add_u32 m0, s100, 0x3000
	v_lshl_add_u64 v[106:107], v[72:73], 0, s[26:27]
	global_load_lds_dwordx4 v[106:107], off
	v_lshl_add_u64 v[72:73], v[72:73], 0, s[44:45]
	s_mov_b64 s[0:1], 0xb00080
	s_add_u32 m0, s100, 0x8000
	v_lshl_add_u64 v[106:107], v[74:75], 0, s[0:1]
	global_load_lds_dwordx4 v[106:107], off
	s_mov_b64 s[0:1], 0xb10080
	s_add_u32 m0, s100, 0x9000
	v_lshl_add_u64 v[106:107], v[74:75], 0, s[0:1]
	global_load_lds_dwordx4 v[106:107], off
	s_mov_b64 s[0:1], 0xb20080
	s_add_u32 m0, s100, 0xa000
	v_lshl_add_u64 v[106:107], v[74:75], 0, s[0:1]
	global_load_lds_dwordx4 v[106:107], off
	s_mov_b64 s[0:1], 0xb30080
	s_add_u32 m0, s100, 0xb000
	v_lshl_add_u64 v[106:107], v[74:75], 0, s[0:1]
	global_load_lds_dwordx4 v[106:107], off
	v_lshl_add_u64 v[74:75], v[74:75], 0, s[44:45]
; template <int EPI, int MI>
; DI void gemm_tile(const GemmDesc& g, int tm, int tn, char* smem) {
;     ...
;   for (int kt = 0; kt < nk; kt += 2) {
;     if (kt + 1 < nk) G_GLDS(kt + 1, 1);
;     G_COMPUTE(0);
;     asm volatile("s_waitcnt vmcnt(0)" ::: "memory");
;     __syncthreads();
;     if (kt + 1 < nk) {
;       if (kt + 2 < nk) G_GLDS(kt + 2, 0);
;       G_COMPUTE(1);
;       asm volatile("s_waitcnt vmcnt(0)" ::: "memory");
;       __syncthreads();
;     }
.Lgc_noearly:
	ds_read_b128 v[240:243], v102 offset:49152
	ds_read_b128 v[244:247], v102 offset:53248
	ds_read_b128 v[224:227], v98 offset:16384
	v_mfma_f32_32x32x16_bf16 v[48:63], v[232:235], v[248:251], v[48:63]
	v_mfma_f32_32x32x16_bf16 v[32:47], v[232:235], v[252:255], v[32:47]
	ds_read_b128 v[228:231], v98 offset:20480
	v_mfma_f32_32x32x16_bf16 v[16:31], v[236:239], v[248:251], v[16:31]
	v_mfma_f32_32x32x16_bf16 v[0:15], v[236:239], v[252:255], v[0:15]
	s_cmp_eq_u32 s101, 14
	s_cbranch_scc1 .Lgc_last
	ds_read_b128 v[248:251], v103 offset:49152
	ds_read_b128 v[252:255], v103 offset:53248
	ds_read_b128 v[232:235], v99 offset:16384
	s_waitcnt lgkmcnt(4)
	v_mfma_f32_32x32x16_bf16 v[48:63], v[224:227], v[240:243], v[48:63]
	v_mfma_f32_32x32x16_bf16 v[32:47], v[224:227], v[244:247], v[32:47]
	ds_read_b128 v[236:239], v99 offset:20480
	s_waitcnt lgkmcnt(4)
	v_mfma_f32_32x32x16_bf16 v[16:31], v[228:231], v[240:243], v[16:31]
	v_mfma_f32_32x32x16_bf16 v[0:15], v[228:231], v[244:247], v[0:15]
	ds_read_b128 v[240:243], v104 offset:49152
	ds_read_b128 v[244:247], v104 offset:53248
	ds_read_b128 v[224:227], v100 offset:16384
	s_waitcnt lgkmcnt(4)
	v_mfma_f32_32x32x16_bf16 v[48:63], v[232:235], v[248:251], v[48:63]
	v_mfma_f32_32x32x16_bf16 v[32:47], v[232:235], v[252:255], v[32:47]
	ds_read_b128 v[228:231], v100 offset:20480
	s_waitcnt lgkmcnt(4)
	v_mfma_f32_32x32x16_bf16 v[16:31], v[236:239], v[248:251], v[16:31]
	v_mfma_f32_32x32x16_bf16 v[0:15], v[236:239], v[252:255], v[0:15]
	ds_read_b128 v[248:251], v105 offset:49152
	ds_read_b128 v[252:255], v105 offset:53248
	ds_read_b128 v[232:235], v101 offset:16384
	s_waitcnt lgkmcnt(4)
	v_mfma_f32_32x32x16_bf16 v[48:63], v[224:227], v[240:243], v[48:63]
	v_mfma_f32_32x32x16_bf16 v[32:47], v[224:227], v[244:247], v[32:47]
	ds_read_b128 v[236:239], v101 offset:20480
	s_waitcnt lgkmcnt(4)
	v_mfma_f32_32x32x16_bf16 v[16:31], v[228:231], v[240:243], v[16:31]
	v_mfma_f32_32x32x16_bf16 v[0:15], v[228:231], v[244:247], v[0:15]
	s_waitcnt lgkmcnt(0)
	s_waitcnt vmcnt(0)
	s_barrier
	s_add_u32 m0, s100, 0x4000
	v_lshl_add_u64 v[106:107], v[72:73], 0, s[96:97]
	global_load_lds_dwordx4 v[106:107], off
	s_add_u32 m0, s100, 0x5000
	v_lshl_add_u64 v[106:107], v[72:73], 0, s[50:51]
	global_load_lds_dwordx4 v[106:107], off
	s_add_u32 m0, s100, 0x6000
	v_lshl_add_u64 v[106:107], v[72:73], 0, s[24:25]
	global_load_lds_dwordx4 v[106:107], off
	s_add_u32 m0, s100, 0x7000
	v_lshl_add_u64 v[106:107], v[72:73], 0, s[26:27]
	global_load_lds_dwordx4 v[106:107], off
	v_lshl_add_u64 v[72:73], v[72:73], 0, s[44:45]
	s_mov_b64 s[0:1], 0xb00080
	s_add_u32 m0, s100, 0xc000
	v_lshl_add_u64 v[106:107], v[74:75], 0, s[0:1]
	global_load_lds_dwordx4 v[106:107], off
	s_mov_b64 s[0:1], 0xb10080
	s_add_u32 m0, s100, 0xd000
	v_lshl_add_u64 v[106:107], v[74:75], 0, s[0:1]
	global_load_lds_dwordx4 v[106:107], off
	s_mov_b64 s[0:1], 0xb20080
	s_add_u32 m0, s100, 0xe000
	v_lshl_add_u64 v[106:107], v[74:75], 0, s[0:1]
	global_load_lds_dwordx4 v[106:107], off
	s_mov_b64 s[0:1], 0xb30080
	s_add_u32 m0, s100, 0xf000
	v_lshl_add_u64 v[106:107], v[74:75], 0, s[0:1]
	global_load_lds_dwordx4 v[106:107], off
	v_lshl_add_u64 v[74:75], v[74:75], 0, s[44:45]
	ds_read_b128 v[240:243], v102 offset:32768
	ds_read_b128 v[244:247], v102 offset:36864
	ds_read_b128 v[224:227], v98
	v_mfma_f32_32x32x16_bf16 v[48:63], v[232:235], v[248:251], v[48:63]
	v_mfma_f32_32x32x16_bf16 v[32:47], v[232:235], v[252:255], v[32:47]
	ds_read_b128 v[228:231], v98 offset:4096
	v_mfma_f32_32x32x16_bf16 v[16:31], v[236:239], v[248:251], v[16:31]
	v_mfma_f32_32x32x16_bf16 v[0:15], v[236:239], v[252:255], v[0:15]
	s_add_u32 s101, s101, 2
	s_branch .Lgc_loop
